# leading half runs its epilogue at priority 1 after the alignment barrier (reset by the next MFMA block or at the unit loop exit), on top of v16
# speedup vs baseline: 1.0009x; 1.0009x over previous
.LBB0_141:
	v_mov_b32_e32 v146, v0
	s_lshl_b32 s1, s50, 11
	v_readfirstlane_b32 s0, v146
	s_ashr_i32 s51, s0, 8
	s_add_i32 s1, s1, 0
	s_lshl_b32 s4, s51, 10
	v_and_b32_e32 v226, 15, v146
	s_add_i32 s1, s1, s4
	v_lshl_add_u32 v130, v226, 6, s1
	v_add_u32_e32 v142, 0x26000, v130
	ds_read_b128 v[130:133], v142
	ds_read_b128 v[134:137], v142 offset:16
	s_and_b64 vcc, exec, s[16:17]
	s_cbranch_vccz .Lalign_l0
	s_barrier
	s_setprio 1

.LBB0_278:
	s_setprio 0
	s_waitcnt vmcnt(0)
	s_barrier

.LBB0_533:
	v_lshl_add_u32 v158, s33, 8, v143
	v_ashrrev_i32_e32 v159, 31, v158
	v_lshl_add_u64 v[152:153], v[158:159], 3, s[4:5]
	global_load_dwordx2 v[154:155], v[152:153], off
	global_load_dwordx2 v[162:163], v[152:153], off offset:128
	global_load_dwordx2 v[164:165], v[152:153], off offset:256
	global_load_dwordx2 v[166:167], v[152:153], off offset:384
	global_load_dwordx2 v[168:169], v[152:153], off offset:1024
	global_load_dwordx2 v[170:171], v[152:153], off offset:1152
	global_load_dwordx2 v[172:173], v[152:153], off offset:1280
	global_load_dwordx2 v[174:175], v[152:153], off offset:1408
	s_and_b64 vcc, exec, s[6:7]
	s_cbranch_vccz .Lalign_l2
	s_barrier
	s_setprio 1

.LBB0_853:
	v_lshl_or_b32 v66, s39, 8, v199
	v_lshl_add_u32 v214, s50, 8, v197
	v_ashrrev_i32_e32 v67, 31, v66
	v_lshlrev_b64 v[216:217], 1, v[66:67]
	v_ashrrev_i32_e32 v215, 31, v214
	v_lshl_add_u64 v[66:67], s[86:87], 0, v[216:217]
	v_lshlrev_b64 v[232:233], 12, v[214:215]
	v_lshl_add_u64 v[68:69], v[66:67], 0, v[232:233]
	global_load_dwordx4 v[190:193], v[68:69], off
	global_load_dwordx4 v[178:181], v[68:69], off offset:256
	v_or_b32_e32 v68, 16, v214
	v_ashrrev_i32_e32 v69, 31, v68
	v_lshlrev_b64 v[230:231], 12, v[68:69]
	v_lshl_add_u64 v[68:69], v[66:67], 0, v[230:231]
	global_load_dwordx4 v[174:177], v[68:69], off
	global_load_dwordx4 v[170:173], v[68:69], off offset:256
	v_or_b32_e32 v68, 32, v214
	v_ashrrev_i32_e32 v69, 31, v68
	v_lshlrev_b64 v[228:229], 12, v[68:69]
	v_lshl_add_u64 v[68:69], v[66:67], 0, v[228:229]
	global_load_dwordx4 v[162:165], v[68:69], off
	global_load_dwordx4 v[158:161], v[68:69], off offset:256
	v_or_b32_e32 v68, 48, v214
	v_ashrrev_i32_e32 v69, 31, v68
	v_lshlrev_b64 v[226:227], 12, v[68:69]
	v_lshl_add_u64 v[68:69], v[66:67], 0, v[226:227]
	global_load_dwordx4 v[154:157], v[68:69], off
	global_load_dwordx4 v[150:153], v[68:69], off offset:256
	s_mov_b64 s[18:19], 0x80000
	v_lshl_add_u64 v[224:225], v[232:233], 0, s[18:19]
	s_mov_b64 s[18:19], 0x90000
	v_lshl_add_u64 v[222:223], v[232:233], 0, s[18:19]
	s_mov_b64 s[18:19], 0xa0000
	v_lshl_add_u64 v[68:69], v[66:67], 0, v[224:225]
	v_lshl_add_u64 v[220:221], v[232:233], 0, s[18:19]
	s_mov_b64 s[18:19], 0xb0000
	global_load_dwordx4 v[142:145], v[68:69], off
	global_load_dwordx4 v[130:133], v[68:69], off offset:256
	v_lshl_add_u64 v[68:69], v[66:67], 0, v[222:223]
	v_lshl_add_u64 v[218:219], v[232:233], 0, s[18:19]
	v_lshl_add_u64 v[232:233], s[86:87], 0, v[232:233]
	global_load_dwordx4 v[118:121], v[68:69], off
	global_load_dwordx4 v[106:109], v[68:69], off offset:256
	v_lshl_add_u64 v[68:69], v[66:67], 0, v[220:221]
	v_lshl_add_u64 v[66:67], v[66:67], 0, v[218:219]
	v_lshl_add_u64 v[232:233], v[232:233], 0, v[216:217]
	global_load_dwordx4 v[98:101], v[68:69], off
	global_load_dwordx4 v[82:85], v[68:69], off offset:256
	global_load_dwordx4 v[78:81], v[66:67], off
	s_nop 0
	global_load_dwordx4 v[66:69], v[66:67], off offset:256
	s_and_b64 vcc, exec, s[14:15]
	s_cbranch_vccz .Lalign_l5
	s_barrier
	s_setprio 1

.LBB0_981:
	s_bfe_u32 s12, s6, 0x20006
	s_mul_i32 s6, s4, 0x3000
	s_lshl_b32 s4, s4, 11
	s_add_i32 s4, s4, 0
	s_lshl_b32 s7, s5, 10
	v_and_b32_e32 v153, 15, v130
	v_lshrrev_b32_e32 v130, 1, v130
	s_add_i32 s4, s4, s7
	v_and_b32_e32 v151, 24, v130
	v_lshl_add_u32 v130, v153, 6, s4
	v_add_u32_e32 v150, 0x26000, v130
	ds_read_b128 v[130:133], v150
	ds_read_b128 v[134:137], v150 offset:16
	ds_read_b128 v[156:159], v150 offset:32
	ds_read_b128 v[160:163], v150 offset:48
	s_and_b64 vcc, exec, s[26:27]
	s_cbranch_vccz .Lalign_l7
	s_barrier
	s_setprio 1

.LBB0_1378:
	s_setprio 0
	s_waitcnt vmcnt(0)
	v_readlane_b32 s76, v254, 49
	v_readlane_b32 s77, v254, 50
	s_mov_b32 s62, 0x18000
	v_readlane_b32 s38, v255, 2
	v_mov_b64_e32 v[244:245], 0x448
	s_barrier
	v_readlane_b32 s39, v255, 3

.LBB0_1444:
	v_lshl_or_b32 v66, s44, 8, v199
	v_lshl_add_u32 v214, s45, 8, v197
	v_ashrrev_i32_e32 v67, 31, v66
	v_lshlrev_b64 v[216:217], 1, v[66:67]
	v_ashrrev_i32_e32 v215, 31, v214
	v_lshl_add_u64 v[66:67], s[86:87], 0, v[216:217]
	v_lshlrev_b64 v[200:201], 12, v[214:215]
	v_lshl_add_u64 v[68:69], v[66:67], 0, v[200:201]
	global_load_dwordx4 v[190:193], v[68:69], off
	global_load_dwordx4 v[178:181], v[68:69], off offset:256
	v_or_b32_e32 v68, 16, v214
	v_ashrrev_i32_e32 v69, 31, v68
	v_lshlrev_b64 v[230:231], 12, v[68:69]
	v_lshl_add_u64 v[68:69], v[66:67], 0, v[230:231]
	global_load_dwordx4 v[174:177], v[68:69], off
	global_load_dwordx4 v[170:173], v[68:69], off offset:256
	v_or_b32_e32 v68, 32, v214
	v_ashrrev_i32_e32 v69, 31, v68
	v_lshlrev_b64 v[228:229], 12, v[68:69]
	v_lshl_add_u64 v[68:69], v[66:67], 0, v[228:229]
	global_load_dwordx4 v[162:165], v[68:69], off
	global_load_dwordx4 v[158:161], v[68:69], off offset:256
	v_or_b32_e32 v68, 48, v214
	v_ashrrev_i32_e32 v69, 31, v68
	v_lshlrev_b64 v[226:227], 12, v[68:69]
	s_mov_b64 s[18:19], 0x80000
	v_lshl_add_u64 v[68:69], v[66:67], 0, v[226:227]
	v_lshl_add_u64 v[224:225], v[200:201], 0, s[18:19]
	s_mov_b64 s[18:19], 0x90000
	global_load_dwordx4 v[154:157], v[68:69], off
	global_load_dwordx4 v[150:153], v[68:69], off offset:256
	v_lshl_add_u64 v[222:223], v[200:201], 0, s[18:19]
	s_mov_b64 s[18:19], 0xa0000
	v_lshl_add_u64 v[220:221], v[200:201], 0, s[18:19]
	s_mov_b64 s[18:19], 0xb0000
	v_lshl_add_u64 v[218:219], v[200:201], 0, s[18:19]
	v_lshl_add_u64 v[200:201], s[86:87], 0, v[200:201]
	v_lshl_add_u64 v[232:233], v[200:201], 0, v[216:217]
	v_lshl_add_u64 v[68:69], v[66:67], 0, v[224:225]
	global_load_dwordx4 v[142:145], v[68:69], off
	global_load_dwordx4 v[130:133], v[68:69], off offset:256
	v_lshl_add_u64 v[68:69], v[66:67], 0, v[222:223]
	global_load_dwordx4 v[118:121], v[68:69], off
	global_load_dwordx4 v[106:109], v[68:69], off offset:256
	v_lshl_add_u64 v[68:69], v[66:67], 0, v[220:221]
	v_lshl_add_u64 v[66:67], v[66:67], 0, v[218:219]
	global_load_dwordx4 v[98:101], v[68:69], off
	global_load_dwordx4 v[86:89], v[68:69], off offset:256
	global_load_dwordx4 v[78:81], v[66:67], off
	s_nop 0
	global_load_dwordx4 v[66:69], v[66:67], off offset:256
	s_and_b64 vcc, exec, s[14:15]
	s_cbranch_vccz .Lalign_l8
	s_barrier
	s_setprio 1

.LBB0_1449:
	s_setprio 0
	s_waitcnt vmcnt(0)
	s_barrier
	s_mov_b32 s89, 0x803f
	s_andn2_b64 vcc, exec, s[6:7]
	s_mov_b64 s[0:1], -1
	s_cbranch_vccnz .LBB0_1428
